# combination: AGPR-pipelined GEMM fragments + no prologue store drain + younger-half setprio + barrier top-generation polling
# baseline (speedup 1.0000x reference)
.LBB0_94:
	s_ashr_i32 s0, s2, 31
	s_lshr_b32 s0, s0, 29
	s_add_i32 s0, s2, s0
	v_mov_b32_e32 v78, v133
	s_and_b32 s1, s0, 0x1fffff8
	s_lshl_b32 s0, s0, 5
	s_and_b32 s22, s0, 0xffffff00
	v_ashrrev_i32_e32 v6, 6, v78
	v_bfe_u32 v7, v78, 3, 3
	v_lshl_or_b32 v8, v6, 5, v7
	v_add_u32_e32 v0, s22, v8
	s_waitcnt lgkmcnt(0)
	v_ashrrev_i32_e32 v1, 31, v0
	v_lshlrev_b64 v[2:3], 11, v[0:1]
	v_bfe_u32 v1, v78, 4, 2
	v_readlane_b32 s20, v214, 4
	v_xor_b32_e32 v1, v1, v78
	v_readlane_b32 s21, v214, 5
	v_lshlrev_b32_e32 v1, 4, v1
	v_and_b32_e32 v64, 0x70, v1
	v_lshl_add_u64 v[2:3], s[20:21], 0, v[2:3]
	v_or_b32_e32 v1, 8, v8
	v_lshl_add_u64 v[66:67], v[2:3], 0, v[64:65]
	v_add_u32_e32 v2, s22, v1
	v_lshrrev_b32_e32 v1, 1, v1
	v_xor_b32_e32 v1, v1, v78
	v_ashrrev_i32_e32 v3, 31, v2
	v_lshlrev_b32_e32 v1, 4, v1
	v_or_b32_e32 v0, 16, v0
	v_lshlrev_b64 v[2:3], 11, v[2:3]
	v_and_b32_e32 v4, 0x70, v1
	v_ashrrev_i32_e32 v1, 31, v0
	v_lshl_add_u64 v[2:3], s[20:21], 0, v[2:3]
	v_mov_b32_e32 v5, v65
	v_lshlrev_b64 v[0:1], 11, v[0:1]
	v_lshl_add_u64 v[68:69], v[2:3], 0, v[4:5]
	v_lshl_add_u64 v[0:1], s[20:21], 0, v[0:1]
	v_or_b32_e32 v2, 24, v8
	v_lshl_add_u64 v[70:71], v[0:1], 0, v[64:65]
	v_add_u32_e32 v0, s22, v2
	v_lshrrev_b32_e32 v2, 1, v2
	v_ashrrev_i32_e32 v1, 31, v0
	v_xor_b32_e32 v2, v2, v78
	v_lshlrev_b64 v[0:1], 11, v[0:1]
	v_lshlrev_b32_e32 v2, 4, v2
	s_sub_i32 s1, s2, s1
	v_lshl_add_u64 v[0:1], s[20:21], 0, v[0:1]
	v_and_b32_e32 v2, 0x70, v2
	v_mov_b32_e32 v3, v65
	s_lshl_b32 s0, s1, 7
	v_lshl_add_u64 v[72:73], v[0:1], 0, v[2:3]
	v_lshl_or_b32 v2, v6, 4, v7
	v_add_u32_e32 v0, s0, v2
	v_lshlrev_b32_e32 v3, 12, v6
	v_ashrrev_i32_e32 v1, 31, v0
	v_add_u32_e32 v126, 0, v3
	v_lshlrev_b64 v[0:1], 11, v[0:1]
	s_nop 0
	v_readfirstlane_b32 s38, v126
	v_add_u32_e32 v127, 0x400, v126
	v_lshl_add_u64 v[0:1], s[40:41], 0, v[0:1]
	v_or_b32_e32 v2, 8, v2
	s_waitcnt lgkmcnt(0)
	s_barrier
	s_mov_b32 m0, s38
	v_readfirstlane_b32 s39, v127
	v_add_u32_e32 v128, 0x800, v126
	v_lshlrev_b32_e32 v5, 11, v6
	v_and_b32_e32 v80, 1, v6
	v_lshl_add_u64 v[74:75], v[0:1], 0, v[64:65]
	v_add_u32_e32 v0, s0, v2
	v_lshrrev_b32_e32 v2, 1, v2
	global_load_lds_dwordx4 v[66:67], off
	s_mov_b32 m0, s39
	v_readfirstlane_b32 s48, v128
	v_add_u32_e32 v129, 0xc00, v126
	v_add_u32_e32 v6, 0, v5
	v_ashrrev_i32_e32 v1, 31, v0
	v_xor_b32_e32 v2, v2, v78
	global_load_lds_dwordx4 v[68:69], off
	s_mov_b32 m0, s48
	v_readfirstlane_b32 s49, v129
	v_add_u32_e32 v131, 0x8000, v6
	v_lshlrev_b64 v[0:1], 11, v[0:1]
	v_lshlrev_b32_e32 v2, 4, v2
	global_load_lds_dwordx4 v[70:71], off
	s_mov_b32 m0, s49
	v_readfirstlane_b32 s53, v131
	v_add_u32_e32 v130, 0x8400, v6
	v_lshl_add_u64 v[0:1], s[40:41], 0, v[0:1]
	v_and_b32_e32 v64, 0x70, v2
	global_load_lds_dwordx4 v[72:73], off
	s_mov_b32 m0, s53
	v_readfirstlane_b32 s54, v130
	v_add_u32_e32 v120, 0xc000, v126
	v_lshl_add_u64 v[76:77], v[0:1], 0, v[64:65]
	global_load_lds_dwordx4 v[74:75], off
	s_mov_b32 m0, s54
	s_mov_b64 s[20:21], 0x80
	v_readfirstlane_b32 s29, v120
	v_add_u32_e32 v121, 0xc400, v126
	global_load_lds_dwordx4 v[76:77], off
	v_lshl_add_u64 v[0:1], v[66:67], 0, s[20:21]
	s_mov_b32 m0, s29
	v_readfirstlane_b32 s33, v121
	v_add_u32_e32 v122, 0xc800, v126
	global_load_lds_dwordx4 v[0:1], off
	v_lshl_add_u64 v[0:1], v[68:69], 0, s[20:21]
	s_mov_b32 m0, s33
	v_readfirstlane_b32 s34, v122
	v_add_u32_e32 v123, 0xcc00, v126
	global_load_lds_dwordx4 v[0:1], off
	v_lshl_add_u64 v[0:1], v[70:71], 0, s[20:21]
	s_mov_b32 m0, s34
	v_readfirstlane_b32 s35, v123
	v_add_u32_e32 v124, s85, v5
	global_load_lds_dwordx4 v[0:1], off
	v_lshl_add_u64 v[0:1], v[72:73], 0, s[20:21]
	s_mov_b32 m0, s35
	v_readfirstlane_b32 s36, v124
	v_add_u32_e32 v125, 0x14400, v6
	global_load_lds_dwordx4 v[0:1], off
	v_lshl_add_u64 v[0:1], v[74:75], 0, s[20:21]
	s_mov_b32 m0, s36
	v_readfirstlane_b32 s37, v125
	global_load_lds_dwordx4 v[0:1], off
	v_lshl_add_u64 v[0:1], v[76:77], 0, s[20:21]
	s_mov_b32 m0, s37
	v_lshrrev_b32_e32 v2, 1, v78
	v_bfe_u32 v64, v78, 5, 1
	global_load_lds_dwordx4 v[0:1], off
	v_add_u32_e32 v114, s3, v3
	v_bitop3_b32 v0, v2, v64, 7 bitop3:0x6c
	s_waitcnt vmcnt(6)
	s_mov_b64 s[30:31], 0x100
	v_readfirstlane_b32 s1, v114
	v_add_u32_e32 v115, 0x400, v114
	v_lshlrev_b32_e32 v132, 4, v0
	s_waitcnt lgkmcnt(0)
	s_barrier
	v_lshl_add_u64 v[0:1], v[66:67], 0, s[30:31]
	s_mov_b32 m0, s1
	v_readfirstlane_b32 s20, v115
	v_add_u32_e32 v116, 0x800, v114
	global_load_lds_dwordx4 v[0:1], off
	v_lshl_add_u64 v[0:1], v[68:69], 0, s[30:31]
	s_mov_b32 m0, s20
	v_readfirstlane_b32 s21, v116
	v_add_u32_e32 v117, 0xc00, v114
	v_readlane_b32 s24, v212, 31
	v_and_b32_e32 v79, 31, v78
	global_load_lds_dwordx4 v[0:1], off
	v_lshl_add_u64 v[0:1], v[70:71], 0, s[30:31]
	s_mov_b32 m0, s21
	v_readfirstlane_b32 s23, v117
	v_add_u32_e32 v118, s24, v5
	v_add_u32_e32 v2, s3, v5
	v_lshlrev_b32_e32 v4, 7, v79
	global_load_lds_dwordx4 v[0:1], off
	v_lshl_add_u64 v[0:1], v[72:73], 0, s[30:31]
	s_mov_b32 m0, s23
	v_readfirstlane_b32 s24, v118
	v_add_u32_e32 v119, 0x8400, v2
	v_lshl_or_b32 v102, v80, 13, v4
	global_load_lds_dwordx4 v[0:1], off
	v_lshl_add_u64 v[0:1], v[74:75], 0, s[30:31]
	s_mov_b32 m0, s24
	v_readfirstlane_b32 s28, v119
	global_load_lds_dwordx4 v[0:1], off
	v_lshl_add_u64 v[0:1], v[76:77], 0, s[30:31]
	s_mov_b32 m0, s28
	v_add_u32_e32 v100, 0, v102
	global_load_lds_dwordx4 v[0:1], off
	v_add_u32_e32 v83, v100, v132
	v_ashrrev_i32_e32 v81, 7, v78
	ds_read_b128 a[0:3], v83 offset:32768
	ds_read_b128 a[4:7], v83 offset:36864
	v_lshl_or_b32 v134, v81, 13, v4
	v_add_u32_e32 v101, 0, v134
	v_add_u32_e32 v82, v101, v132
	ds_read_b128 a[8:11], v82
	ds_read_b128 a[12:15], v82 offset:4096
	v_lshrrev_b32_e32 v182, 6, v133
	s_nop 0
	v_readfirstlane_b32 s32, v182
	s_cmp_ge_u32 s32, 4
	s_cbranch_scc0 .Lmy_prio0
	s_setprio 1

.LBB0_159:
	v_mov_b32_e32 v78, v133
	s_lshl_b32 s22, s2, 8
	v_ashrrev_i32_e32 v6, 6, v78
	v_bfe_u32 v7, v78, 3, 3
	v_lshl_or_b32 v8, v6, 5, v7
	v_add_u32_e32 v0, s22, v8
	s_waitcnt lgkmcnt(0)
	v_ashrrev_i32_e32 v1, 31, v0
	v_lshlrev_b64 v[2:3], 11, v[0:1]
	v_bfe_u32 v1, v78, 4, 2
	v_readlane_b32 s0, v214, 4
	v_xor_b32_e32 v1, v1, v78
	v_readlane_b32 s1, v214, 5
	v_lshlrev_b32_e32 v1, 4, v1
	v_and_b32_e32 v64, 0x70, v1
	v_lshl_add_u64 v[2:3], s[0:1], 0, v[2:3]
	v_or_b32_e32 v1, 8, v8
	v_lshl_add_u64 v[66:67], v[2:3], 0, v[64:65]
	v_add_u32_e32 v2, s22, v1
	v_lshrrev_b32_e32 v1, 1, v1
	v_xor_b32_e32 v1, v1, v78
	v_ashrrev_i32_e32 v3, 31, v2
	v_lshlrev_b32_e32 v1, 4, v1
	v_or_b32_e32 v0, 16, v0
	v_lshlrev_b64 v[2:3], 11, v[2:3]
	v_and_b32_e32 v4, 0x70, v1
	v_ashrrev_i32_e32 v1, 31, v0
	v_lshl_add_u64 v[2:3], s[0:1], 0, v[2:3]
	v_mov_b32_e32 v5, v65
	v_lshlrev_b64 v[0:1], 11, v[0:1]
	v_lshl_add_u64 v[68:69], v[2:3], 0, v[4:5]
	v_lshl_add_u64 v[0:1], s[0:1], 0, v[0:1]
	v_or_b32_e32 v2, 24, v8
	v_lshl_add_u64 v[70:71], v[0:1], 0, v[64:65]
	v_add_u32_e32 v0, s22, v2
	v_lshrrev_b32_e32 v2, 1, v2
	v_ashrrev_i32_e32 v1, 31, v0
	v_xor_b32_e32 v2, v2, v78
	v_lshlrev_b64 v[0:1], 11, v[0:1]
	v_lshlrev_b32_e32 v2, 4, v2
	v_lshl_add_u64 v[0:1], s[0:1], 0, v[0:1]
	v_and_b32_e32 v2, 0x70, v2
	v_mov_b32_e32 v3, v65
	v_lshl_add_u64 v[72:73], v[0:1], 0, v[2:3]
	v_lshl_or_b32 v2, v6, 4, v7
	v_readlane_b32 s31, v214, 58
	v_lshlrev_b32_e32 v3, 12, v6
	v_add_u32_e32 v126, 0, v3
	v_add_u32_e32 v0, s31, v2
	v_ashrrev_i32_e32 v1, 31, v0
	v_lshlrev_b64 v[0:1], 11, v[0:1]
	s_nop 0
	v_readfirstlane_b32 s37, v126
	v_add_u32_e32 v127, 0x400, v126
	v_lshl_add_u64 v[0:1], s[40:41], 0, v[0:1]
	v_or_b32_e32 v2, 8, v2
	s_waitcnt lgkmcnt(0)
	s_barrier
	s_mov_b32 m0, s37
	v_readfirstlane_b32 s38, v127
	v_add_u32_e32 v128, 0x800, v126
	v_lshlrev_b32_e32 v5, 11, v6
	v_and_b32_e32 v80, 1, v6
	v_lshl_add_u64 v[74:75], v[0:1], 0, v[64:65]
	v_add_u32_e32 v0, s31, v2
	v_lshrrev_b32_e32 v2, 1, v2
	global_load_lds_dwordx4 v[66:67], off
	s_mov_b32 m0, s38
	v_readfirstlane_b32 s39, v128
	v_add_u32_e32 v129, 0xc00, v126
	v_add_u32_e32 v6, 0, v5
	v_ashrrev_i32_e32 v1, 31, v0
	v_xor_b32_e32 v2, v2, v78
	global_load_lds_dwordx4 v[68:69], off
	s_mov_b32 m0, s39
	v_readfirstlane_b32 s48, v129
	v_add_u32_e32 v131, 0x8000, v6
	v_lshlrev_b64 v[0:1], 11, v[0:1]
	v_lshlrev_b32_e32 v2, 4, v2
	global_load_lds_dwordx4 v[70:71], off
	s_mov_b32 m0, s48
	v_readfirstlane_b32 s49, v131
	v_add_u32_e32 v130, 0x8400, v6
	v_lshl_add_u64 v[0:1], s[40:41], 0, v[0:1]
	v_and_b32_e32 v64, 0x70, v2
	global_load_lds_dwordx4 v[72:73], off
	s_mov_b32 m0, s49
	v_readfirstlane_b32 s53, v130
	v_add_u32_e32 v120, 0xc000, v126
	v_lshl_add_u64 v[76:77], v[0:1], 0, v[64:65]
	global_load_lds_dwordx4 v[74:75], off
	s_mov_b32 m0, s53
	s_mov_b64 s[0:1], 0x80
	v_readfirstlane_b32 s28, v120
	v_add_u32_e32 v121, 0xc400, v126
	global_load_lds_dwordx4 v[76:77], off
	v_lshl_add_u64 v[0:1], v[66:67], 0, s[0:1]
	s_mov_b32 m0, s28
	v_readfirstlane_b32 s29, v121
	v_add_u32_e32 v122, 0xc800, v126
	global_load_lds_dwordx4 v[0:1], off
	v_lshl_add_u64 v[0:1], v[68:69], 0, s[0:1]
	s_mov_b32 m0, s29
	v_readfirstlane_b32 s33, v122
	v_add_u32_e32 v123, 0xcc00, v126
	global_load_lds_dwordx4 v[0:1], off
	v_lshl_add_u64 v[0:1], v[70:71], 0, s[0:1]
	s_mov_b32 m0, s33
	v_readfirstlane_b32 s34, v123
	v_add_u32_e32 v124, s85, v5
	global_load_lds_dwordx4 v[0:1], off
	v_lshl_add_u64 v[0:1], v[72:73], 0, s[0:1]
	s_mov_b32 m0, s34
	v_readfirstlane_b32 s35, v124
	v_add_u32_e32 v125, 0x14400, v6
	global_load_lds_dwordx4 v[0:1], off
	v_lshl_add_u64 v[0:1], v[74:75], 0, s[0:1]
	s_mov_b32 m0, s35
	v_readfirstlane_b32 s36, v125
	global_load_lds_dwordx4 v[0:1], off
	v_lshl_add_u64 v[0:1], v[76:77], 0, s[0:1]
	s_mov_b32 m0, s36
	v_lshrrev_b32_e32 v2, 1, v78
	v_bfe_u32 v64, v78, 5, 1
	global_load_lds_dwordx4 v[0:1], off
	v_add_u32_e32 v114, s3, v3
	v_bitop3_b32 v0, v2, v64, 7 bitop3:0x6c
	s_waitcnt vmcnt(6)
	s_mov_b64 s[46:47], 0x100
	v_readfirstlane_b32 s0, v114
	v_add_u32_e32 v115, 0x400, v114
	v_lshlrev_b32_e32 v132, 4, v0
	s_waitcnt lgkmcnt(0)
	s_barrier
	v_lshl_add_u64 v[0:1], v[66:67], 0, s[46:47]
	s_mov_b32 m0, s0
	v_readfirstlane_b32 s1, v115
	v_add_u32_e32 v116, 0x800, v114
	global_load_lds_dwordx4 v[0:1], off
	v_lshl_add_u64 v[0:1], v[68:69], 0, s[46:47]
	s_mov_b32 m0, s1
	v_readfirstlane_b32 s20, v116
	v_add_u32_e32 v117, 0xc00, v114
	v_readlane_b32 s23, v212, 31
	v_and_b32_e32 v79, 31, v78
	global_load_lds_dwordx4 v[0:1], off
	v_lshl_add_u64 v[0:1], v[70:71], 0, s[46:47]
	s_mov_b32 m0, s20
	v_readfirstlane_b32 s21, v117
	v_add_u32_e32 v118, s23, v5
	v_add_u32_e32 v2, s3, v5
	v_lshlrev_b32_e32 v4, 7, v79
	global_load_lds_dwordx4 v[0:1], off
	v_lshl_add_u64 v[0:1], v[72:73], 0, s[46:47]
	s_mov_b32 m0, s21
	v_readfirstlane_b32 s23, v118
	v_add_u32_e32 v119, 0x8400, v2
	v_lshl_or_b32 v102, v80, 13, v4
	global_load_lds_dwordx4 v[0:1], off
	v_lshl_add_u64 v[0:1], v[74:75], 0, s[46:47]
	s_mov_b32 m0, s23
	v_readfirstlane_b32 s24, v119
	global_load_lds_dwordx4 v[0:1], off
	v_lshl_add_u64 v[0:1], v[76:77], 0, s[46:47]
	s_mov_b32 m0, s24
	v_add_u32_e32 v100, 0, v102
	global_load_lds_dwordx4 v[0:1], off
	v_add_u32_e32 v83, v100, v132
	v_ashrrev_i32_e32 v81, 7, v78
	ds_read_b128 a[0:3], v83 offset:32768
	ds_read_b128 a[4:7], v83 offset:36864
	v_lshl_or_b32 v134, v81, 13, v4
	v_add_u32_e32 v101, 0, v134
	v_add_u32_e32 v82, v101, v132
	ds_read_b128 a[8:11], v82
	ds_read_b128 a[12:15], v82 offset:4096
	v_lshrrev_b32_e32 v182, 6, v133
	s_nop 0
	v_readfirstlane_b32 s32, v182
	s_cmp_ge_u32 s32, 4
	s_cbranch_scc0 .Lmy_prio1
	s_setprio 1
